# attention: removed the compiler's vmcnt(0) at each unit start (no longer waits for the previous unit's O stores before issuing the bias-table loads); on top of peeled GEMM first iteration etc
# baseline (speedup 1.0000x reference)
.LBB0_60:
	s_ashr_i32 s11, s10, 31
	s_lshl_b32 s19, s40, 8
	s_lshl_b64 s[2:3], s[10:11], 15
	s_add_u32 s12, s30, s2
	v_mov_b32_e32 v68, v196
	s_addc_u32 s13, s31, s3
	s_add_i32 s20, s19, 0x100
	s_ashr_i32 s14, s20, 2
	v_mov_b32_e32 v16, v68
	v_readfirstlane_b32 s46, v68
	v_mov_b32_e32 v0, 0
	v_cmp_gt_i32_e32 vcc, s14, v16
	v_mov_b32_e32 v4, 0
	v_mov_b32_e32 v5, 0
	v_mov_b32_e32 v6, 0
	v_mov_b32_e32 v7, 0
	s_and_saveexec_b64 s[2:3], vcc
	s_cbranch_execz .LBB0_62
	v_ashrrev_i32_e32 v17, 31, v16
	v_lshl_add_u64 v[2:3], v[16:17], 4, s[12:13]
	flat_load_dwordx4 v[4:7], v[2:3]
